# in-proj tile order rebalanced: silu N-tiles spread evenly over workgroup classes (pn^=2 for pn>=8)
# baseline (speedup 1.0000x reference)
.LBB0_355:
	s_add_i32 s39, s39, 1
	s_mul_i32 s0, s39, s93
	s_mul_hi_u32 s1, s39, s24
	s_add_i32 s1, s1, s0
	s_mul_i32 s0, s39, s24
	s_add_u32 s56, s0, s28
	v_readlane_b32 s0, v254, 42
	s_addc_u32 s57, s1, s0
	s_waitcnt lgkmcnt(0)
	v_mov_b64_e32 v[0:1], 0x600
	v_cmp_lt_i64_e64 s[0:1], s[56:57], v[0:1]
	v_mov_b64_e32 v[0:1], 0x5ff
	v_cmp_gt_i64_e32 vcc, s[56:57], v[0:1]
	s_cbranch_vccnz .LBB0_357
	s_ashr_i32 s16, s56, 31
	s_lshr_b32 s16, s16, 29
	s_add_i32 s16, s56, s16
	s_ashr_i32 s17, s16, 3
	s_and_b32 s16, s16, -8
	s_sub_i32 s16, s56, s16
	s_cmp_lt_i32 s16, 0
	s_movk_i32 s25, 0xc1
	s_cselect_b32 s25, s25, 0xc0
	s_mul_i32 s16, s16, s25
	s_add_i32 s16, s16, s17
	s_mul_hi_i32 s17, s16, 0x2aaaaaab
	s_lshr_b32 s25, s17, 31
	s_ashr_i32 s17, s17, 4
	s_add_i32 s17, s17, s25
	s_lshl_b32 s25, s17, 3
	s_sub_i32 s26, 0x80, s25
	s_min_i32 s26, s26, 8
	s_abs_i32 s27, s26
	v_cvt_f32_u32_e32 v0, s27
	s_sub_i32 s53, 0, s27
	s_mulk_i32 s17, 0x60
	s_sub_i32 s16, s16, s17
	v_rcp_iflag_f32_e32 v0, v0
	s_abs_i32 s17, s16
	s_xor_b32 s52, s16, s26
	s_ashr_i32 s52, s52, 31
	v_mul_f32_e32 v0, 0x4f7ffffe, v0
	v_cvt_u32_f32_e32 v0, v0
	s_nop 0
	v_readfirstlane_b32 s54, v0
	s_mul_i32 s53, s53, s54
	s_mul_hi_u32 s53, s54, s53
	s_add_i32 s54, s54, s53
	s_mul_hi_u32 s53, s17, s54
	s_mul_i32 s54, s53, s27
	s_sub_i32 s17, s17, s54
	s_add_i32 s55, s53, 1
	s_sub_i32 s54, s17, s27
	s_cmp_ge_u32 s17, s27
	s_cselect_b32 s53, s55, s53
	s_cselect_b32 s17, s54, s17
	s_add_i32 s54, s53, 1
	s_cmp_ge_u32 s17, s27
	s_cselect_b32 s17, s54, s53
	s_xor_b32 s17, s17, s52
	s_sub_i32 s52, s17, s52
	s_mul_i32 s17, s52, s26
	s_sub_i32 s16, s16, s17
	s_add_i32 s54, s25, s16
	s_cmpk_gt_i32 s52, 7
	s_cselect_b32 s17, 2, 0
	s_xor_b32 s52, s52, s17
